# SWA unit prologue: first K/V LDS-DMA tile issued without waiting for the q-fragment and sink loads (as in the MLA units)
# speedup vs baseline: 1.0045x; 1.0045x over previous
; template <int MODE>
; __device__ __forceinline__ void attn_unit(unsigned char* ws_, const float* rpb, const float* sink, int l, int h, int qb, int kvq, unsigned char* lds_g) {
;     ...
;   int T0, T1, tw0, tw1, wrow = 0, qcol = 0, c0 = 0; float slope2 = 0.f;
;   if (MODE == 1) { T0 = tw0 = kvq * (S / 64 / KVSPLIT); T1 = tw1 = T0 + S / 64 / KVSPLIT; }
;   else if (MODE == 0) { const int R = qb * 4; T0 = min(max(R - 4, 0), 120); T1 = min(max(R - 1, 0), 120) + 8; wrow = R + (wid >> 1); tw0 = min(max(wrow - 4, 0), 120); tw1 = tw0 + 8;
;                         qcol = (wid & 1) * 32 + r32; c0 = min(max(qcol - 8, 0), 48); }
;   else { T0 = max(0, (q0 - 128) >> 6); T1 = min(S / 64, ((q0 + 255 + 128) >> 6) + 1); const int qw = q0 + wid * 32; tw0 = max(0, (qw - 128) >> 6); tw1 = min(S / 64, ((qw + 31 + 128) >> 6) + 1);
;          slope2 = exp2f(-8.0f * (float)(h + 1) / 6.0f) * LOG2E; }
;   LAS float* wsl = (LAS float*)(ldl + OFF_WS) + wid * 64; LAS float* li_l = wsl; LAS float* al_l = wsl + 32;
;   LAS float* rpbL = (LAS float*)(ldl + OFF_RPB);
;   if (MODE == 0) { for (int i = tid; i < 465; i += NTHREADS) rpbL[i] = rpb[(l * 4 + h) * 465 + i] * LOG2E; }
;   float m_reg = -1e29f, l_reg = 0.f;
;   if (MODE == 2) { m_reg = sink[l * 6 + h] * LOG2E; l_reg = hi == 0 ? 1.f : 0.f; }
;   f32x16 o[4] = {}; bf16x8 qr[ND];
;   { const bf16_t* Qw = Qp + (size_t)qi * ldq + hi * 8;
; #pragma unroll
;     for (int d0 = 0; d0 < ND; ++d0) qr[d0] = *(const bf16x8*)(Qw + d0 * 16); }
;   unsigned kg[NCH], vg[2];
; #pragma unroll
;   for (int i = 0; i < NCH; ++i) { const int X = (wid + 8 * i) * 1024 + lane * 16, row = X / (DQK * 2), cs = X % (DQK * 2), colB = cs ^ kswz_x<DQK>(row); kg[i] = (unsigned)(row * ldk + (colB >> 1)) * 2u; }
; #pragma unroll
;   for (int i = 0; i < 2; ++i) { const int X = (wid + 8 * i) * 1024 + lane * 16, st = X >> 9, w = X & 511, kk = ((st >> 2) << 3) | (w >> 6), c = ((st & 3) << 5) | ((w & 63) >> 1);
;     const int k = kk;
;     vg[i] = (unsigned)(k * ldv + c) * 2u; }
;   const int vb0 = (int)(uintptr_t)lds_g + v_rd_base(lane);
;   const int kbase0 = (int)(uintptr_t)lds_g + OFF_K;
;   constexpr int NKO = DQK == 192 ? 4 : ND;
;   int ko[NKO];
; #pragma unroll
;   for (int d0 = 0; d0 < NKO; ++d0) ko[d0] = kswz<DQK>(r32, (d0 * 16 + hi * 8) * 2);
;     ...
;   const int wslab = __builtin_amdgcn_readfirstlane(wid) * 1024;
;     ...
;   __syncthreads();
.LBB0_780:
	s_and_b64 s[0:1], s[6:7], exec
	s_cselect_b32 s0, s57, s58
	s_cmp_lt_i32 s0, 0
	s_cbranch_scc1 .LBB0_779
	v_readlane_b32 s1, v254, 43
	s_lshr_b32 s12, s0, 5
	s_mov_b32 s13, 0x40c00000
	v_mov_b32_e32 v0, s1
	ds_read_b64 v[2:3], v0
	v_readlane_b32 s1, v254, 24
	v_mov_b32_e32 v11, v216
	s_waitcnt lgkmcnt(0)
	v_readfirstlane_b32 s8, v2
	v_mov_b32_e32 v0, s1
	s_lshl_b32 s1, s12, 8
	v_readfirstlane_b32 s9, v3
	s_add_u32 s1, s8, s1
	s_addc_u32 s3, s9, 0
	s_add_u32 s2, s1, 0x11829280
	s_addc_u32 s3, s3, 0
	s_mul_hi_u32 s1, s0, 0xaaaaaaab
	s_lshl_b32 s0, s0, 8
	s_and_b32 s10, s0, 0x1f00
	s_add_i32 s0, s12, 1
	ds_read_b64 v[4:5], v0
	v_cvt_f32_u32_e32 v0, s0
	s_lshl_b32 s1, s1, 1
	s_and_b32 s90, s1, 0xffffff80
	s_add_i32 s11, s10, 0xffffff80
	v_mul_f32_e32 v0, 0xc1000000, v0
	v_div_scale_f32 v2, s[0:1], s13, s13, v0
	v_rcp_f32_e32 v3, v2
	s_waitcnt lgkmcnt(0)
	v_readfirstlane_b32 s4, v4
	s_add_i32 s0, s10, 0x17f
	s_lshr_b32 s14, s0, 6
	v_fma_f32 v4, -v2, v3, 1.0
	v_fmac_f32_e32 v3, v4, v3
	v_div_scale_f32 v4, vcc, v0, s13, v0
	v_readlane_b32 s0, v254, 46
	v_readfirstlane_b32 s5, v5
	v_mul_f32_e32 v5, v4, v3
	v_readlane_b32 s1, v254, 47
	s_mul_i32 s0, s0, 6
	v_fma_f32 v6, -v2, v5, v4
	s_add_i32 s0, s12, s0
	s_mov_b32 s1, s91
	s_ashr_i32 s11, s11, 6
	v_fmac_f32_e32 v5, v6, v3
	s_lshl_b64 s[0:1], s[0:1], 2
	v_fma_f32 v2, -v2, v5, v4
	s_add_u32 s0, s4, s0
	v_div_fmas_f32 v2, v2, v3, v5
	v_ashrrev_i32_e32 v177, 6, v11
	s_addc_u32 s1, s5, s1
	v_and_b32_e32 v199, 31, v11
	v_lshl_add_u32 v176, v177, 5, s10
	v_div_fixup_f32 v13, v2, s13, v0
	v_mov_b64_e32 v[2:3], s[0:1]
	v_bfe_u32 v198, v11, 5, 1
	v_or_b32_e32 v10, v176, v199
	flat_load_dword v17, v[2:3]
	v_mov_b64_e32 v[2:3], s[2:3]
	s_movk_i32 s0, 0x1e00
	v_mad_i64_i32 v[4:5], s[0:1], v10, s0, v[2:3]
	v_lshlrev_b32_e32 v2, 4, v198
	v_mov_b32_e32 v3, v1
	v_and_b32_e32 v12, 63, v11
	v_lshl_add_u64 v[4:5], v[4:5], 0, v[2:3]
	flat_load_dwordx4 v[144:147], v[4:5]
	flat_load_dwordx4 v[148:151], v[4:5] offset:32
	flat_load_dwordx4 v[152:155], v[4:5] offset:64
	flat_load_dwordx4 v[156:159], v[4:5] offset:96
	flat_load_dwordx4 v[160:163], v[4:5] offset:128
	flat_load_dwordx4 v[164:167], v[4:5] offset:160
	flat_load_dwordx4 v[168:171], v[4:5] offset:192
	flat_load_dwordx4 v[172:175], v[4:5] offset:224
	v_lshlrev_b32_e32 v5, 10, v177
	v_lshlrev_b32_e32 v19, 4, v12
	v_or_b32_e32 v3, v5, v19
	v_bfe_i32 v0, v177, 21, 1
	v_add_u32_sdwa v0, v3, v0 dst_sel:DWORD dst_unused:UNUSED_PAD src0_sel:DWORD src1_sel:BYTE_3
	v_ashrrev_i32_e32 v0, 8, v0
	v_and_b32_e32 v6, 7, v0
	v_lshrrev_b32_e32 v7, 1, v0
	v_mul_i32_i24_e32 v4, 0x100, v0
	v_and_or_b32 v6, v7, 8, v6
	v_sub_u32_e32 v4, v3, v4
	v_lshlrev_b32_e32 v6, 4, v6
	v_mul_i32_i24_e32 v0, 0x1e00, v0
	v_add_u32_e32 v3, 0x2000, v3
	s_lshl_b64 s[2:3], s[90:91], 1
	v_xad_u32 v0, v6, v4, v0
	v_ashrrev_i32_e32 v4, 31, v3
	s_add_u32 s15, s8, s2
	v_add_u32_sdwa v4, v3, v4 dst_sel:DWORD dst_unused:UNUSED_PAD src0_sel:DWORD src1_sel:BYTE_3
	s_addc_u32 s20, s9, s3
	v_ashrrev_i32_e32 v4, 8, v4
	s_add_u32 s17, s15, 0x11829880
	s_mov_b32 s0, 0xc2fc0000
	v_mul_i32_i24_e32 v6, 0x100, v4
	s_addc_u32 s18, s20, 0
	s_max_i32 s13, s11, 0
	v_cmp_gt_f32_e64 s[0:1], s0, v13
	v_sub_u32_e32 v3, v3, v6
	v_and_b32_e32 v6, 7, v4
	v_lshrrev_b32_e32 v7, 1, v4
	s_and_b64 s[4:5], s[0:1], exec
	v_and_or_b32 v6, v7, 8, v6
	v_ashrrev_i32_e32 v18, 8, v5
	v_add_u32_e32 v5, 0x2000, v5
	s_cselect_b32 s16, 0xffffffc0, 0
	v_lshlrev_b32_e32 v6, 4, v6
	v_mul_i32_i24_e32 v4, 0x1e00, v4
	s_min_u32 s14, s14, 0x7f
	v_bfe_u32 v14, v11, 2, 3
	s_mov_b32 s4, 0xfffff8
	v_ashrrev_i32_e32 v20, 8, v5
	v_xad_u32 v4, v6, v3, v4
	v_and_or_b32 v6, v18, s4, v14
	v_and_or_b32 v5, v20, s4, v14
	s_add_u32 s19, s15, 0x11829a80
	v_readfirstlane_b32 s4, v177
	s_addc_u32 s21, s20, 0
	s_lshl_b32 s15, s4, 10
	s_mul_i32 s20, s13, 0x78000
	s_add_u32 s4, s17, s20
	v_lshlrev_b32_e32 v21, 3, v12
	s_addc_u32 s5, s18, 0
	s_add_i32 s15, s15, 0
	v_and_b32_e32 v3, 32, v11
	v_and_b32_e32 v16, 64, v11
	v_and_b32_e32 v15, 24, v21
	s_add_i32 m0, s15, 0xc000
	v_or3_b32 v7, v15, v3, v16
	v_mul_u32_u24_e32 v6, 0xf00, v6
	s_barrier
	global_load_lds_dwordx4 v0, s[4:5]
	s_add_i32 m0, s15, 0xe000
	v_or_b32_e32 v6, v6, v7
	v_mul_u32_u24_e32 v5, 0xf00, v5
	global_load_lds_dwordx4 v4, s[4:5]
	s_add_u32 s4, s19, s20
	v_lshlrev_b32_e32 v6, 1, v6
	v_or_b32_e32 v5, v5, v7
	s_addc_u32 s5, s21, 0
	s_mov_b32 m0, s15
	v_lshlrev_b32_e32 v8, 1, v5
	global_load_lds_dwordx4 v6, s[4:5]
	s_add_i32 m0, s15, 0x2000
	s_cmp_ge_i32 s11, s14
	global_load_lds_dwordx4 v8, s[4:5]
	s_mov_b64 s[4:5], -1
	s_cbranch_scc0 .LBB0_783
	s_waitcnt vmcnt(0)
	s_mov_b64 s[4:5], 0
